# the five GEMM K-loop heads aligned to 128 bytes (.p2align 7)
# speedup vs baseline: 1.0037x; 1.0003x over previous
; template <class Epi, class Sched, bool ALIGN_EPI = false, bool SP2 = false>
; __device__ __forceinline__ void gemm_phase(PG8_LAS unsigned char* lds, const Gemm g, const Sched& S, const Epi& E) {
;     ...
;         const bool has_next = S.next(ui + 1, nxt);
;         const char* nA = has_next ? (const char*)g.A + (size_t)nxt.pm * tstep : cA; const char* nB = has_next ? (const char*)g.Bt + (size_t)nxt.pn * tstep : cB;
;         for (int t = 0; t < nt; t += 2) {
;             const bool last = (t == nt - 2);
;             const char* a1 = cA + (size_t)(t + 1) * kstep;
;             const char* a2 = last ? nA : cA + (size_t)(t + 2) * kstep; const char* b2 = last ? nB : cB + (size_t)(t + 2) * kstep;
;             const char* a3 = a2 + kstep; const char* b3 = b2 + kstep;
;             if (last && has_next) S.a_ready(nxt);
.LBB0_169:
	s_add_u32 s93, s46, 0x100
	s_addc_u32 s94, s47, 0
	s_ashr_i32 s69, s68, 31
	s_lshl_b64 s[4:5], s[68:69], 20
	s_add_u32 s76, s52, s4
	s_addc_u32 s77, s53, s5
	s_and_b64 s[4:5], s[38:39], exec
	s_cselect_b32 s4, s77, s71
	s_cselect_b32 s5, s76, s70
	s_ashr_i32 s63, s62, 31
	s_lshl_b64 s[6:7], s[62:63], 20
	v_readlane_b32 s8, v249, 19
	v_readlane_b32 s9, v249, 20
	s_add_u32 s72, s8, s6
	s_addc_u32 s73, s9, s7
	s_and_b64 s[6:7], s[38:39], exec
	s_cselect_b32 s6, s73, s47
	s_cselect_b32 s7, s72, s46
	s_add_u32 s8, s70, 0x80080
	s_addc_u32 s9, s71, 0
	v_lshl_add_u64 v[144:145], s[8:9], 0, v[140:141]
	v_lshl_add_u64 v[146:147], s[8:9], 0, v[142:143]
	s_mov_b32 s8, -2
	s_mov_b64 s[46:47], 0
	.p2align 7

; template <class Epi, class Sched, bool ALIGN_EPI = false, bool SP2 = false>
; __device__ __forceinline__ void gemm_phase(PG8_LAS unsigned char* lds, const Gemm g, const Sched& S, const Epi& E) {
;     ...
;         const bool has_next = S.next(ui + 1, nxt);
;         const char* nA = has_next ? (const char*)g.A + (size_t)nxt.pm * tstep : cA; const char* nB = has_next ? (const char*)g.Bt + (size_t)nxt.pn * tstep : cB;
;         for (int t = 0; t < nt; t += 2) {
;             const bool last = (t == nt - 2);
;             const char* a1 = cA + (size_t)(t + 1) * kstep;
;             const char* a2 = last ? nA : cA + (size_t)(t + 2) * kstep; const char* b2 = last ? nB : cB + (size_t)(t + 2) * kstep;
;             const char* a3 = a2 + kstep; const char* b3 = b2 + kstep;
;             if (last && has_next) S.a_ready(nxt);
;     ...
; #pragma unroll
;         for (int a = 0; a < 2; ++a)
; #pragma unroll
;             for (int b = 0; b < 2; ++b)
; #pragma unroll
;                 for (int m = 0; m < 4; ++m)
; #pragma unroll
;                     for (int n = 0; n < 2; ++n) acc[a][b][m][n] = (f32x4){0.f, 0.f, 0.f, 0.f};
.LBB0_787:
	s_ashr_i32 s63, s62, 31
	s_lshl_b64 s[4:5], s[62:63], 18
	v_readlane_b32 s6, v249, 4
	v_readlane_b32 s7, v249, 5
	s_add_u32 s70, s6, s4
	s_addc_u32 s71, s7, s5
	s_and_b64 s[4:5], s[78:79], exec
	s_cselect_b32 s36, s71, s69
	s_cselect_b32 s37, s70, s68
	s_ashr_i32 s55, s54, 31
	s_lshl_b64 s[4:5], s[54:55], 18
	v_readlane_b32 s6, v249, 7
	v_readlane_b32 s7, v249, 8
	s_add_u32 s84, s6, s4
	s_addc_u32 s85, s7, s5
	s_and_b64 s[4:5], s[78:79], exec
	s_cselect_b32 s4, s85, s73
	s_cselect_b32 s5, s84, s72
	s_add_u32 s68, s68, 0x20080
	s_addc_u32 s69, s69, 0
	s_add_u32 s6, s72, 0x100
	v_mov_b32_e32 v2, 0
	s_addc_u32 s7, s73, 0
	s_mov_b32 s8, -2
	v_mov_b32_e32 v3, v2
	v_mov_b32_e32 v4, v2
	v_mov_b32_e32 v5, v2
	v_mov_b32_e32 v6, v2
	v_mov_b32_e32 v7, v2
	v_mov_b32_e32 v8, v2
	v_mov_b32_e32 v9, v2
	v_mov_b32_e32 v18, v2
	v_mov_b32_e32 v19, v2
	v_mov_b32_e32 v20, v2
	v_mov_b32_e32 v21, v2
	v_mov_b32_e32 v22, v2
	v_mov_b32_e32 v23, v2
	v_mov_b32_e32 v24, v2
	v_mov_b32_e32 v25, v2
	v_mov_b32_e32 v42, v2
	v_mov_b32_e32 v43, v2
	v_mov_b32_e32 v44, v2
	v_mov_b32_e32 v45, v2
	v_mov_b32_e32 v46, v2
	v_mov_b32_e32 v47, v2
	v_mov_b32_e32 v48, v2
	v_mov_b32_e32 v49, v2
	v_mov_b32_e32 v66, v2
	v_mov_b32_e32 v67, v2
	v_mov_b32_e32 v68, v2
	v_mov_b32_e32 v69, v2
	v_mov_b32_e32 v70, v2
	v_mov_b32_e32 v71, v2
	v_mov_b32_e32 v72, v2
	v_mov_b32_e32 v73, v2
	v_mov_b32_e32 v10, v2
	v_mov_b32_e32 v11, v2
	v_mov_b32_e32 v12, v2
	v_mov_b32_e32 v13, v2
	v_mov_b32_e32 v14, v2
	v_mov_b32_e32 v15, v2
	v_mov_b32_e32 v16, v2
	v_mov_b32_e32 v17, v2
	v_mov_b32_e32 v26, v2
	v_mov_b32_e32 v27, v2
	v_mov_b32_e32 v28, v2
	v_mov_b32_e32 v29, v2
	v_mov_b32_e32 v30, v2
	v_mov_b32_e32 v31, v2
	v_mov_b32_e32 v32, v2
	v_mov_b32_e32 v33, v2
	v_mov_b32_e32 v58, v2
	v_mov_b32_e32 v59, v2
	v_mov_b32_e32 v60, v2
	v_mov_b32_e32 v61, v2
	v_mov_b32_e32 v62, v2
	v_mov_b32_e32 v63, v2
	v_mov_b32_e32 v64, v2
	v_mov_b32_e32 v65, v2
	v_mov_b32_e32 v74, v2
	v_mov_b32_e32 v75, v2
	v_mov_b32_e32 v76, v2
	v_mov_b32_e32 v77, v2
	v_mov_b32_e32 v78, v2
	v_mov_b32_e32 v79, v2
	v_mov_b32_e32 v80, v2
	v_mov_b32_e32 v81, v2
	v_mov_b32_e32 v82, v2
	v_mov_b32_e32 v83, v2
	v_mov_b32_e32 v84, v2
	v_mov_b32_e32 v85, v2
	v_mov_b32_e32 v86, v2
	v_mov_b32_e32 v87, v2
	v_mov_b32_e32 v88, v2
	v_mov_b32_e32 v89, v2
	v_mov_b32_e32 v98, v2
	v_mov_b32_e32 v99, v2
	v_mov_b32_e32 v100, v2
	v_mov_b32_e32 v101, v2
	v_mov_b32_e32 v102, v2
	v_mov_b32_e32 v103, v2
	v_mov_b32_e32 v104, v2
	v_mov_b32_e32 v105, v2
	v_mov_b32_e32 v118, v2
	v_mov_b32_e32 v119, v2
	v_mov_b32_e32 v120, v2
	v_mov_b32_e32 v121, v2
	v_mov_b32_e32 v122, v2
	v_mov_b32_e32 v123, v2
	v_mov_b32_e32 v124, v2
	v_mov_b32_e32 v125, v2
	v_mov_b32_e32 v142, v2
	v_mov_b32_e32 v143, v2
	v_mov_b32_e32 v144, v2
	v_mov_b32_e32 v145, v2
	v_mov_b32_e32 v146, v2
	v_mov_b32_e32 v147, v2
	v_mov_b32_e32 v148, v2
	v_mov_b32_e32 v149, v2
	v_mov_b32_e32 v90, v2
	v_mov_b32_e32 v91, v2
	v_mov_b32_e32 v92, v2
	v_mov_b32_e32 v93, v2
	v_mov_b32_e32 v94, v2
	v_mov_b32_e32 v95, v2
	v_mov_b32_e32 v96, v2
	v_mov_b32_e32 v97, v2
	v_mov_b32_e32 v106, v2
	v_mov_b32_e32 v107, v2
	v_mov_b32_e32 v108, v2
	v_mov_b32_e32 v109, v2
	v_mov_b32_e32 v110, v2
	v_mov_b32_e32 v111, v2
	v_mov_b32_e32 v112, v2
	v_mov_b32_e32 v113, v2
	v_mov_b32_e32 v130, v2
	v_mov_b32_e32 v131, v2
	v_mov_b32_e32 v132, v2
	v_mov_b32_e32 v133, v2
	v_mov_b32_e32 v134, v2
	v_mov_b32_e32 v135, v2
	v_mov_b32_e32 v136, v2
	v_mov_b32_e32 v137, v2
	v_mov_b32_e32 v162, v2
	v_mov_b32_e32 v163, v2
	v_mov_b32_e32 v164, v2
	v_mov_b32_e32 v165, v2
	v_mov_b32_e32 v166, v2
	v_mov_b32_e32 v167, v2
	v_mov_b32_e32 v168, v2
	v_mov_b32_e32 v169, v2
	.p2align 7

; template <class Epi, class Sched, bool ALIGN_EPI = false, bool SP2 = false>
; __device__ __forceinline__ void gemm_phase(PG8_LAS unsigned char* lds, const Gemm g, const Sched& S, const Epi& E) {
;     ...
;         const bool has_next = S.next(ui + 1, nxt);
;         const char* nA = has_next ? (const char*)g.A + (size_t)nxt.pm * tstep : cA; const char* nB = has_next ? (const char*)g.Bt + (size_t)nxt.pn * tstep : cB;
;         for (int t = 0; t < nt; t += 2) {
;             const bool last = (t == nt - 2);
;             const char* a1 = cA + (size_t)(t + 1) * kstep;
;             const char* a2 = last ? nA : cA + (size_t)(t + 2) * kstep; const char* b2 = last ? nB : cB + (size_t)(t + 2) * kstep;
;             const char* a3 = a2 + kstep; const char* b3 = b2 + kstep;
;             if (last && has_next) S.a_ready(nxt);
;     ...
; #pragma unroll
;         for (int a = 0; a < 2; ++a)
; #pragma unroll
;             for (int b = 0; b < 2; ++b)
; #pragma unroll
;                 for (int m = 0; m < 4; ++m)
; #pragma unroll
;                     for (int n = 0; n < 2; ++n) acc[a][b][m][n] = (f32x4){0.f, 0.f, 0.f, 0.f};
.LBB0_926:
	s_ashr_i32 s73, s72, 31
	s_lshl_b64 s[4:5], s[72:73], 20
	v_readlane_b32 s6, v249, 9
	v_readlane_b32 s7, v249, 10
	s_add_u32 s76, s6, s4
	s_addc_u32 s77, s7, s5
	s_and_b64 s[4:5], s[92:93], exec
	s_cselect_b32 s36, s77, s39
	s_cselect_b32 s37, s76, s38
	s_ashr_i32 s69, s68, 31
	s_lshl_b64 s[4:5], s[68:69], 20
	v_readlane_b32 s6, v249, 17
	v_readlane_b32 s7, v249, 18
	s_add_u32 s80, s6, s4
	s_addc_u32 s81, s7, s5
	s_and_b64 s[4:5], s[92:93], exec
	s_cselect_b32 s4, s81, s47
	s_cselect_b32 s5, s80, s46
	s_add_u32 s38, s38, 0x80080
	s_addc_u32 s39, s39, 0
	s_add_u32 s6, s46, 0x100
	v_mov_b32_e32 v2, 0
	s_addc_u32 s7, s47, 0
	s_mov_b32 s8, -2
	v_mov_b32_e32 v3, v2
	v_mov_b32_e32 v4, v2
	v_mov_b32_e32 v5, v2
	v_mov_b32_e32 v6, v2
	v_mov_b32_e32 v7, v2
	v_mov_b32_e32 v8, v2
	v_mov_b32_e32 v9, v2
	v_mov_b32_e32 v18, v2
	v_mov_b32_e32 v19, v2
	v_mov_b32_e32 v20, v2
	v_mov_b32_e32 v21, v2
	v_mov_b32_e32 v22, v2
	v_mov_b32_e32 v23, v2
	v_mov_b32_e32 v24, v2
	v_mov_b32_e32 v25, v2
	v_mov_b32_e32 v34, v2
	s_waitcnt lgkmcnt(0)
	v_mov_b32_e32 v35, v2
	v_mov_b32_e32 v36, v2
	v_mov_b32_e32 v37, v2
	v_mov_b32_e32 v38, v2
	v_mov_b32_e32 v39, v2
	v_mov_b32_e32 v40, v2
	v_mov_b32_e32 v41, v2
	v_mov_b32_e32 v50, v2
	v_mov_b32_e32 v51, v2
	v_mov_b32_e32 v52, v2
	v_mov_b32_e32 v53, v2
	v_mov_b32_e32 v54, v2
	v_mov_b32_e32 v55, v2
	v_mov_b32_e32 v56, v2
	v_mov_b32_e32 v57, v2
	v_mov_b32_e32 v10, v2
	v_mov_b32_e32 v11, v2
	v_mov_b32_e32 v12, v2
	v_mov_b32_e32 v13, v2
	v_mov_b32_e32 v14, v2
	v_mov_b32_e32 v15, v2
	v_mov_b32_e32 v16, v2
	v_mov_b32_e32 v17, v2
	v_mov_b32_e32 v26, v2
	v_mov_b32_e32 v27, v2
	v_mov_b32_e32 v28, v2
	v_mov_b32_e32 v29, v2
	v_mov_b32_e32 v30, v2
	v_mov_b32_e32 v31, v2
	v_mov_b32_e32 v32, v2
	v_mov_b32_e32 v33, v2
	v_mov_b32_e32 v42, v2
	v_mov_b32_e32 v43, v2
	v_mov_b32_e32 v44, v2
	v_mov_b32_e32 v45, v2
	v_mov_b32_e32 v46, v2
	v_mov_b32_e32 v47, v2
	v_mov_b32_e32 v48, v2
	v_mov_b32_e32 v49, v2
	v_mov_b32_e32 v58, v2
	v_mov_b32_e32 v59, v2
	v_mov_b32_e32 v60, v2
	v_mov_b32_e32 v61, v2
	v_mov_b32_e32 v62, v2
	v_mov_b32_e32 v63, v2
	v_mov_b32_e32 v64, v2
	v_mov_b32_e32 v65, v2
	v_mov_b32_e32 v74, v2
	v_mov_b32_e32 v75, v2
	v_mov_b32_e32 v76, v2
	v_mov_b32_e32 v77, v2
	v_mov_b32_e32 v82, v2
	v_mov_b32_e32 v83, v2
	v_mov_b32_e32 v84, v2
	v_mov_b32_e32 v85, v2
	v_mov_b32_e32 v98, v2
	v_mov_b32_e32 v99, v2
	v_mov_b32_e32 v100, v2
	v_mov_b32_e32 v101, v2
	v_mov_b32_e32 v102, v2
	v_mov_b32_e32 v103, v2
	v_mov_b32_e32 v104, v2
	v_mov_b32_e32 v105, v2
	v_mov_b32_e32 v114, v2
	v_mov_b32_e32 v115, v2
	v_mov_b32_e32 v116, v2
	v_mov_b32_e32 v117, v2
	v_mov_b32_e32 v118, v2
	v_mov_b32_e32 v119, v2
	v_mov_b32_e32 v120, v2
	v_mov_b32_e32 v121, v2
	v_mov_b32_e32 v130, v2
	v_mov_b32_e32 v131, v2
	v_mov_b32_e32 v132, v2
	v_mov_b32_e32 v133, v2
	v_mov_b32_e32 v134, v2
	v_mov_b32_e32 v135, v2
	v_mov_b32_e32 v136, v2
	v_mov_b32_e32 v137, v2
	v_mov_b32_e32 v90, v2
	v_mov_b32_e32 v91, v2
	v_mov_b32_e32 v92, v2
	v_mov_b32_e32 v93, v2
	v_mov_b32_e32 v94, v2
	v_mov_b32_e32 v95, v2
	v_mov_b32_e32 v96, v2
	v_mov_b32_e32 v97, v2
	v_mov_b32_e32 v106, v2
	v_mov_b32_e32 v107, v2
	v_mov_b32_e32 v108, v2
	v_mov_b32_e32 v109, v2
	v_mov_b32_e32 v110, v2
	v_mov_b32_e32 v111, v2
	v_mov_b32_e32 v112, v2
	v_mov_b32_e32 v113, v2
	v_mov_b32_e32 v122, v2
	v_mov_b32_e32 v123, v2
	v_mov_b32_e32 v124, v2
	v_mov_b32_e32 v125, v2
	v_mov_b32_e32 v126, v2
	v_mov_b32_e32 v127, v2
	v_mov_b32_e32 v128, v2
	v_mov_b32_e32 v129, v2
	v_mov_b32_e32 v138, v2
	v_mov_b32_e32 v139, v2
	v_mov_b32_e32 v140, v2
	v_mov_b32_e32 v141, v2
	v_mov_b32_e32 v142, v2
	v_mov_b32_e32 v143, v2
	v_mov_b32_e32 v144, v2
	v_mov_b32_e32 v145, v2
	.p2align 7

; template <class Epi, class Sched, bool ALIGN_EPI = false, bool SP2 = false>
; __device__ __forceinline__ void gemm_phase(PG8_LAS unsigned char* lds, const Gemm g, const Sched& S, const Epi& E) {
;     ...
;         const bool has_next = S.next(ui + 1, nxt);
;         const char* nA = has_next ? (const char*)g.A + (size_t)nxt.pm * tstep : cA; const char* nB = has_next ? (const char*)g.Bt + (size_t)nxt.pn * tstep : cB;
;         for (int t = 0; t < nt; t += 2) {
;             const bool last = (t == nt - 2);
;             const char* a1 = cA + (size_t)(t + 1) * kstep;
;             const char* a2 = last ? nA : cA + (size_t)(t + 2) * kstep; const char* b2 = last ? nB : cB + (size_t)(t + 2) * kstep;
;             const char* a3 = a2 + kstep; const char* b3 = b2 + kstep;
;             if (last && has_next) S.a_ready(nxt);
;     ...
; #pragma unroll
;         for (int a = 0; a < 2; ++a)
; #pragma unroll
;             for (int b = 0; b < 2; ++b)
; #pragma unroll
;                 for (int m = 0; m < 4; ++m)
; #pragma unroll
;                     for (int n = 0; n < 2; ++n) acc[a][b][m][n] = (f32x4){0.f, 0.f, 0.f, 0.f};
.LBB0_1070:
	s_ashr_i32 s97, s96, 31
	s_lshl_b64 s[4:5], s[96:97], 22
	s_add_u32 s26, s0, s4
	s_addc_u32 s27, s1, s5
	s_and_b64 s[4:5], s[92:93], exec
	s_cselect_b32 s97, s27, s39
	s_cselect_b32 s4, s26, s38
	s_ashr_i32 s85, s84, 31
	s_lshl_b64 s[6:7], s[84:85], 22
	s_add_u32 s94, s56, s6
	s_addc_u32 s95, s57, s7
	s_and_b64 s[6:7], s[92:93], exec
	s_cselect_b32 s5, s95, s47
	s_cselect_b32 s6, s94, s46
	s_add_u32 s38, s38, 0x200080
	s_addc_u32 s39, s39, 0
	s_add_u32 s7, s46, 0x100
	v_mov_b32_e32 v2, 0
	s_addc_u32 s8, s47, 0
	s_mov_b32 s9, -2
	s_waitcnt lgkmcnt(0)
	v_mov_b32_e32 v3, v2
	v_mov_b32_e32 v4, v2
	v_mov_b32_e32 v5, v2
	v_mov_b32_e32 v6, v2
	v_mov_b32_e32 v7, v2
	v_mov_b32_e32 v8, v2
	v_mov_b32_e32 v9, v2
	v_mov_b32_e32 v18, v2
	v_mov_b32_e32 v19, v2
	v_mov_b32_e32 v20, v2
	v_mov_b32_e32 v21, v2
	v_mov_b32_e32 v22, v2
	v_mov_b32_e32 v23, v2
	v_mov_b32_e32 v24, v2
	v_mov_b32_e32 v25, v2
	v_mov_b32_e32 v34, v2
	v_mov_b32_e32 v35, v2
	v_mov_b32_e32 v36, v2
	v_mov_b32_e32 v37, v2
	v_mov_b32_e32 v38, v2
	v_mov_b32_e32 v39, v2
	v_mov_b32_e32 v40, v2
	v_mov_b32_e32 v41, v2
	v_mov_b32_e32 v50, v2
	v_mov_b32_e32 v51, v2
	v_mov_b32_e32 v52, v2
	v_mov_b32_e32 v53, v2
	v_mov_b32_e32 v54, v2
	v_mov_b32_e32 v55, v2
	v_mov_b32_e32 v56, v2
	v_mov_b32_e32 v57, v2
	v_mov_b32_e32 v10, v2
	v_mov_b32_e32 v11, v2
	v_mov_b32_e32 v12, v2
	v_mov_b32_e32 v13, v2
	v_mov_b32_e32 v14, v2
	v_mov_b32_e32 v15, v2
	v_mov_b32_e32 v16, v2
	v_mov_b32_e32 v17, v2
	v_mov_b32_e32 v26, v2
	v_mov_b32_e32 v27, v2
	v_mov_b32_e32 v28, v2
	v_mov_b32_e32 v29, v2
	v_mov_b32_e32 v30, v2
	v_mov_b32_e32 v31, v2
	v_mov_b32_e32 v32, v2
	v_mov_b32_e32 v33, v2
	v_mov_b32_e32 v42, v2
	v_mov_b32_e32 v43, v2
	v_mov_b32_e32 v44, v2
	v_mov_b32_e32 v45, v2
	v_mov_b32_e32 v46, v2
	v_mov_b32_e32 v47, v2
	v_mov_b32_e32 v48, v2
	v_mov_b32_e32 v49, v2
	v_mov_b32_e32 v58, v2
	v_mov_b32_e32 v59, v2
	v_mov_b32_e32 v60, v2
	v_mov_b32_e32 v61, v2
	v_mov_b32_e32 v62, v2
	v_mov_b32_e32 v63, v2
	v_mov_b32_e32 v64, v2
	v_mov_b32_e32 v65, v2
	v_mov_b32_e32 v66, v2
	v_mov_b32_e32 v67, v2
	v_mov_b32_e32 v68, v2
	v_mov_b32_e32 v69, v2
	v_mov_b32_e32 v70, v2
	v_mov_b32_e32 v71, v2
	v_mov_b32_e32 v72, v2
	v_mov_b32_e32 v73, v2
	v_mov_b32_e32 v82, v2
	v_mov_b32_e32 v83, v2
	v_mov_b32_e32 v84, v2
	v_mov_b32_e32 v85, v2
	v_mov_b32_e32 v86, v2
	v_mov_b32_e32 v87, v2
	v_mov_b32_e32 v88, v2
	v_mov_b32_e32 v89, v2
	v_mov_b32_e32 v98, v2
	v_mov_b32_e32 v99, v2
	v_mov_b32_e32 v100, v2
	v_mov_b32_e32 v101, v2
	v_mov_b32_e32 v102, v2
	v_mov_b32_e32 v103, v2
	v_mov_b32_e32 v104, v2
	v_mov_b32_e32 v105, v2
	v_mov_b32_e32 v114, v2
	v_mov_b32_e32 v115, v2
	v_mov_b32_e32 v116, v2
	v_mov_b32_e32 v117, v2
	v_mov_b32_e32 v118, v2
	v_mov_b32_e32 v119, v2
	v_mov_b32_e32 v120, v2
	v_mov_b32_e32 v121, v2
	v_mov_b32_e32 v74, v2
	v_mov_b32_e32 v75, v2
	v_mov_b32_e32 v76, v2
	v_mov_b32_e32 v77, v2
	v_mov_b32_e32 v78, v2
	v_mov_b32_e32 v79, v2
	v_mov_b32_e32 v80, v2
	v_mov_b32_e32 v81, v2
	v_mov_b32_e32 v90, v2
	v_mov_b32_e32 v91, v2
	v_mov_b32_e32 v92, v2
	v_mov_b32_e32 v93, v2
	v_mov_b32_e32 v94, v2
	v_mov_b32_e32 v95, v2
	v_mov_b32_e32 v96, v2
	v_mov_b32_e32 v97, v2
	v_mov_b32_e32 v106, v2
	v_mov_b32_e32 v107, v2
	v_mov_b32_e32 v108, v2
	v_mov_b32_e32 v109, v2
	v_mov_b32_e32 v110, v2
	v_mov_b32_e32 v111, v2
	v_mov_b32_e32 v112, v2
	v_mov_b32_e32 v113, v2
	v_mov_b32_e32 v122, v2
	v_mov_b32_e32 v123, v2
	v_mov_b32_e32 v124, v2
	v_mov_b32_e32 v125, v2
	v_mov_b32_e32 v126, v2
	v_mov_b32_e32 v127, v2
	v_mov_b32_e32 v128, v2
	v_mov_b32_e32 v129, v2
	.p2align 7

; template <class Epi, class Sched, bool ALIGN_EPI = false, bool SP2 = false>
; __device__ __forceinline__ void gemm_phase(PG8_LAS unsigned char* lds, const Gemm g, const Sched& S, const Epi& E) {
;     ...
;         const bool has_next = S.next(ui + 1, nxt);
;         const char* nA = has_next ? (const char*)g.A + (size_t)nxt.pm * tstep : cA; const char* nB = has_next ? (const char*)g.Bt + (size_t)nxt.pn * tstep : cB;
;         for (int t = 0; t < nt; t += 2) {
;             const bool last = (t == nt - 2);
;             const char* a1 = cA + (size_t)(t + 1) * kstep;
;             const char* a2 = last ? nA : cA + (size_t)(t + 2) * kstep; const char* b2 = last ? nB : cB + (size_t)(t + 2) * kstep;
;             const char* a3 = a2 + kstep; const char* b3 = b2 + kstep;
;             if (last && has_next) S.a_ready(nxt);
.LBB0_1232:
	s_add_u32 s36, s80, 0x100
	s_addc_u32 s37, s81, 0
	s_ashr_i32 s73, s72, 31
	s_lshl_b64 s[4:5], s[72:73], 20
	s_add_u32 s78, s0, s4
	s_addc_u32 s79, s1, s5
	s_and_b64 s[4:5], s[46:47], exec
	s_cselect_b32 s4, s79, s69
	s_cselect_b32 s5, s78, s68
	s_ashr_i32 s71, s70, 31
	s_lshl_b64 s[6:7], s[70:71], 20
	s_add_u32 s76, s34, s6
	s_addc_u32 s77, s35, s7
	s_and_b64 s[6:7], s[46:47], exec
	s_cselect_b32 s6, s77, s81
	s_cselect_b32 s7, s76, s80
	s_add_u32 s8, s68, 0x80080
	s_addc_u32 s9, s69, 0
	v_lshl_add_u64 v[140:141], s[8:9], 0, v[136:137]
	v_lshl_add_u64 v[142:143], s[8:9], 0, v[138:139]
	s_mov_b32 s8, -2
	s_mov_b64 s[80:81], 0
	.p2align 7
